# v111 + first grid barrier reads the 16 per-XCD arrival counters with back-to-back loads and one wait (was 15 serialized round trips)
# baseline (speedup 1.0000x reference)
.LBB0_1488:
	s_mov_b64 s[4:5], -1
	v_readlane_b32 s2, v250, 20
	v_readlane_b32 s3, v250, 21
	s_nop 4
	global_load_dword v0, v31, s[2:3] sc1
	v_readlane_b32 s2, v250, 22
	v_readlane_b32 s3, v250, 23
	s_nop 4
	global_load_dword v1, v31, s[2:3] sc1
	v_readlane_b32 s2, v250, 24
	v_readlane_b32 s3, v250, 25
	s_nop 4
	global_load_dword v2, v31, s[2:3] sc1
	v_readlane_b32 s2, v250, 26
	v_readlane_b32 s3, v250, 27
	s_nop 4
	global_load_dword v3, v31, s[2:3] sc1
	v_readlane_b32 s2, v250, 28
	v_readlane_b32 s3, v250, 29
	s_nop 4
	global_load_dword v4, v31, s[2:3] sc1
	v_readlane_b32 s2, v250, 30
	v_readlane_b32 s3, v250, 31
	s_nop 4
	global_load_dword v5, v31, s[2:3] sc1
	v_readlane_b32 s2, v250, 32
	v_readlane_b32 s3, v250, 33
	s_nop 4
	global_load_dword v6, v31, s[2:3] sc1
	v_readlane_b32 s2, v250, 34
	v_readlane_b32 s3, v250, 35
	s_nop 4
	global_load_dword v7, v31, s[2:3] sc1
	v_readlane_b32 s2, v250, 36
	v_readlane_b32 s3, v250, 37
	s_nop 4
	global_load_dword v8, v31, s[2:3] sc1
	v_readlane_b32 s2, v250, 38
	v_readlane_b32 s3, v250, 39
	s_nop 4
	global_load_dword v9, v31, s[2:3] sc1
	v_readlane_b32 s2, v250, 40
	v_readlane_b32 s3, v250, 41
	s_nop 4
	global_load_dword v10, v31, s[2:3] sc1
	v_readlane_b32 s2, v250, 42
	v_readlane_b32 s3, v250, 43
	s_nop 4
	global_load_dword v11, v31, s[2:3] sc1
	v_readlane_b32 s2, v250, 44
	v_readlane_b32 s3, v250, 45
	s_nop 4
	global_load_dword v12, v31, s[2:3] sc1
	v_readlane_b32 s2, v250, 46
	v_readlane_b32 s3, v250, 47
	s_nop 4
	global_load_dword v13, v31, s[2:3] sc1
	v_readlane_b32 s2, v250, 48
	v_readlane_b32 s3, v250, 49
	s_nop 4
	global_load_dword v14, v31, s[2:3] sc1
	v_readlane_b32 s2, v250, 50
	v_readlane_b32 s3, v250, 51
	s_nop 4
	global_load_dword v15, v31, s[2:3] sc1
	s_mov_b64 s[2:3], -1
	s_waitcnt vmcnt(0)
	v_add_u32_e32 v16, v1, v0
	v_add_u32_e32 v16, v16, v2
	v_add_u32_e32 v16, v16, v3
	v_add_u32_e32 v16, v16, v4
	v_add_u32_e32 v16, v16, v5
	v_add_u32_e32 v16, v16, v6
	v_add_u32_e32 v16, v16, v7
	v_add_u32_e32 v16, v16, v8
	v_add_u32_e32 v16, v16, v9
	v_add_u32_e32 v16, v16, v10
	v_add_u32_e32 v16, v16, v11
	v_add_u32_e32 v16, v16, v12
	v_add_u32_e32 v16, v16, v13
	v_add_u32_e32 v16, v16, v14
	v_add_u32_e32 v16, v16, v15
	v_cmp_eq_u32_e32 vcc, s8, v16
	s_cbranch_vccnz .LBB0_1487
	s_and_b32 s2, s9, 0xff
	s_cmp_eq_u32 s2, 0
	s_mov_b64 s[2:3], -1
	s_mov_b64 s[6:7], -1
	s_sleep 1
	s_cbranch_scc0 .LBB0_1492
	v_readlane_b32 s2, v250, 18
	v_readlane_b32 s3, v250, 19
	s_nop 4
	global_load_dword v16, v31, s[2:3] sc1
	s_waitcnt vmcnt(0)
	v_cmp_eq_u32_e32 vcc, 0, v16
	s_cbranch_vccnz .LBB0_1494
	s_mov_b64 s[6:7], 0
	s_mov_b64 s[2:3], -1
